# 7.12 trim: stop-flag test at each DF/SB step start reduced from a 7-instruction ballot (cndmask/readfirstlane/bitcmp/cselect) to one v_cmp into the SGPR pair
# speedup vs baseline: 1.0061x; 1.0009x over previous
.LBB0_364:
	s_and_b32 s90, s86, 8
	s_xor_b32 s82, s90, 8
	s_lshl_b32 s82, s82, 2
	s_add_i32 s82, s82, 0
	s_add_i32 s82, s82, 0x241c0
	v_mov_b32_e32 v82, s82
	ds_read_b128 v[136:139], v82
	ds_read_b128 v[140:143], v82 offset:16
	s_waitcnt lgkmcnt(0)
	v_and_b32_e32 v136, v136, v137
	v_and_b32_e32 v138, v138, v139
	v_and_b32_e32 v140, v140, v141
	v_and_b32_e32 v142, v142, v143
	v_and_b32_e32 v136, v136, v138
	v_and_b32_e32 v140, v140, v142
	v_and_b32_e32 v82, v136, v140
	v_cmp_ne_u32_e64 s[82:83], 0, v82
	s_and_b64 vcc, exec, s[82:83]
	s_cbranch_vccnz .LBB0_355
	s_cmp_lt_i32 s84, 3
	s_cbranch_scc0 .LBB0_373
	s_andn2_b64 vcc, exec, s[72:73]
	s_cbranch_vccz .LBB0_374

.LBB0_404:
	s_mov_b32 s97, s96
	s_waitcnt lgkmcnt(0)
	v_cmp_eq_u64_e64 s[8:9], s[96:97], v[14:15]
	s_and_b64 vcc, exec, s[8:9]
	s_cbranch_vccnz .LBB0_420
	s_cmp_gt_i32 s12, s21
	s_cbranch_scc1 .LBB0_417
	s_xor_b64 s[12:13], s[10:11], -1
	s_add_i32 s10, s27, 0xffff4000
	s_and_b32 s10, s10, 0xc000
	s_add_i32 s14, s34, s10
	v_add_u32_e32 v0, s14, v222
	s_mov_b64 s[10:11], -1
	s_and_b64 vcc, exec, s[12:13]
	v_add_u32_e32 v202, v0, v223
	v_add_u32_e32 v15, v0, v224
	v_add_u32_e32 v14, v0, v225
	v_add_u32_e32 v0, v0, v233
	s_cbranch_vccz .LBB0_408
	ds_read_b128 v[80:83], v202
	ds_read_b128 v[84:87], v202 offset:4096
	ds_read_b128 v[148:151], v15
	ds_read_b128 v[204:207], v15 offset:4096
	ds_read_b128 v[208:211], v14
	ds_read_b128 v[212:215], v14 offset:4096
	ds_read_b128 v[238:241], v0
	ds_read_b128 v[242:245], v0 offset:4096
	s_waitcnt lgkmcnt(7)
	v_mfma_f32_32x32x16_bf16 v[96:111], v[80:83], v[136:139], 0
	s_mov_b64 s[10:11], 0
	s_waitcnt lgkmcnt(6)
	v_mfma_f32_32x32x16_bf16 v[80:95], v[84:87], v[136:139], 0
	s_waitcnt lgkmcnt(5)
	v_mfma_f32_32x32x16_bf16 v[96:111], v[148:151], v[128:131], v[96:111]
	s_waitcnt lgkmcnt(4)
	v_mfma_f32_32x32x16_bf16 v[80:95], v[204:207], v[128:131], v[80:95]
	s_waitcnt lgkmcnt(3)
	v_mfma_f32_32x32x16_bf16 v[96:111], v[208:211], v[140:143], v[96:111]
	s_waitcnt lgkmcnt(2)
	v_mfma_f32_32x32x16_bf16 v[80:95], v[212:215], v[140:143], v[80:95]
	s_waitcnt lgkmcnt(1)
	v_mfma_f32_32x32x16_bf16 v[96:111], v[238:241], v[132:135], v[96:111]
	s_waitcnt lgkmcnt(0)
	v_mfma_f32_32x32x16_bf16 v[80:95], v[242:245], v[132:135], v[80:95]

.LBB0_437:
	s_mov_b32 s97, s96
	s_waitcnt lgkmcnt(0)
	v_cmp_eq_u64_e64 s[8:9], s[96:97], v[2:3]
	s_and_b64 vcc, exec, s[8:9]
	s_cbranch_vccnz .LBB0_449
	s_cmp_gt_i32 s15, s21
	s_cbranch_scc1 .LBB0_446
	s_add_i32 s8, s13, 0xffff4000
	s_and_b32 s8, s8, 0xc000
	v_add_u32_e32 v0, s8, v221
	v_add_u32_e32 v6, v0, v222
	v_add_u32_e32 v14, v0, v223
	ds_read_b128 v[2:5], v6
	ds_read_b128 v[6:9], v6 offset:4096
	ds_read_b128 v[10:13], v14
	ds_read_b128 v[128:131], v14 offset:4096
	v_add_u32_e32 v14, v0, v224
	v_add_u32_e32 v0, v0, v219
	ds_read_b128 v[132:135], v14
	ds_read_b128 v[136:139], v14 offset:4096
	ds_read_b128 v[144:147], v0
	ds_read_b128 v[148:151], v0 offset:4096
	s_add_i32 s8, s12, s10
	s_lshl_b32 s9, s14, 14
	s_waitcnt lgkmcnt(7)
	v_mfma_f32_32x32x16_bf16 v[96:111], v[2:5], v[112:115], 0
	v_add_u32_e32 v235, s9, v220
	s_waitcnt lgkmcnt(6)
	v_mfma_f32_32x32x16_bf16 v[80:95], v[6:9], v[112:115], 0
	s_waitcnt lgkmcnt(5)
	v_mfma_f32_32x32x16_bf16 v[96:111], v[10:13], v[116:119], v[96:111]
	s_waitcnt lgkmcnt(4)
	v_mfma_f32_32x32x16_bf16 v[80:95], v[128:131], v[116:119], v[80:95]
	ds_read_b64_tr_b16 v[6:7], v235
	ds_read_b64_tr_b16 v[8:9], v235 offset:512
	ds_read_b64_tr_b16 v[2:3], v235 offset:1024
	ds_read_b64_tr_b16 v[4:5], v235 offset:1536
	ds_read_b64_tr_b16 v[140:141], v235 offset:4096
	ds_read_b64_tr_b16 v[142:143], v235 offset:4608
	ds_read_b64_tr_b16 v[128:129], v235 offset:5120
	ds_read_b64_tr_b16 v[130:131], v235 offset:5632
	s_waitcnt lgkmcnt(11)
	v_mfma_f32_32x32x16_bf16 v[96:111], v[132:135], v[120:123], v[96:111]
	s_waitcnt lgkmcnt(10)
	v_mfma_f32_32x32x16_bf16 v[80:95], v[136:139], v[120:123], v[80:95]
	s_waitcnt lgkmcnt(9)
	v_mfma_f32_32x32x16_bf16 v[96:111], v[144:147], v[124:127], v[96:111]
	ds_read_b64_tr_b16 v[136:137], v235 offset:2048
	ds_read_b64_tr_b16 v[138:139], v235 offset:2560
	ds_read_b64_tr_b16 v[10:11], v235 offset:3072
	ds_read_b64_tr_b16 v[12:13], v235 offset:3584
	ds_read_b64_tr_b16 v[144:145], v235 offset:6144
	ds_read_b64_tr_b16 v[146:147], v235 offset:6656
	ds_read_b64_tr_b16 v[132:133], v235 offset:7168
	ds_read_b64_tr_b16 v[134:135], v235 offset:7680
	s_waitcnt lgkmcnt(14)
	v_mfma_f32_32x32x16_bf16 v[80:95], v[148:151], v[124:127], v[80:95]
	v_add_u32_e32 v0, v233, v218
	v_cvt_f32_i32_e32 v0, v0
	s_cmp_lg_u32 s8, 1
	s_mov_b64 s[8:9], -1
	s_cbranch_scc0 .LBB0_441
	v_add_f32_e32 v14, 0, v96
	v_subrev_f32_e32 v15, s4, v97
	s_nop 4
	v_fma_f32 v186, s2, v196, v80
	v_fma_f32 v187, s3, v197, v81
	v_fma_f32 v184, s2, v226, v98
	v_fma_f32 v185, s3, v227, v99
	v_max_f32_e32 v148, v14, v186
	v_max_f32_e32 v149, v15, v187
	v_fma_f32 v188, s2, v152, v82
	v_fma_f32 v189, s3, v153, v83
	v_max3_f32 v148, v148, s82, v149
	v_max_f32_e32 v149, v184, v188
	v_max_f32_e32 v150, v185, v189
	v_fma_f32 v190, s2, v154, v100
	v_fma_f32 v191, s3, v155, v101
	v_fma_f32 v192, s2, v156, v84
	v_fma_f32 v193, s3, v157, v85
	v_max3_f32 v148, v148, v149, v150
	v_max_f32_e32 v149, v190, v192
	v_max_f32_e32 v150, v191, v193
	v_fma_f32 v194, s2, v158, v102
	v_fma_f32 v195, s3, v159, v103
	v_fma_f32 v198, s2, v160, v86
	v_fma_f32 v199, s3, v161, v87
	v_max3_f32 v148, v148, v149, v150
	v_max_f32_e32 v149, v194, v198
	v_max_f32_e32 v150, v195, v199
	v_fma_f32 v200, s2, v162, v104
	v_fma_f32 v201, s3, v163, v105
	v_fma_f32 v202, s2, v164, v88
	v_fma_f32 v203, s3, v165, v89
	v_max3_f32 v148, v148, v149, v150
	v_max_f32_e32 v149, v200, v202
	v_max_f32_e32 v150, v201, v203
	v_fma_f32 v204, s2, v166, v106
	v_fma_f32 v205, s3, v167, v107
	v_fma_f32 v206, s2, v168, v90
	v_fma_f32 v207, s3, v169, v91
	v_max3_f32 v148, v148, v149, v150
	v_max_f32_e32 v149, v204, v206
	v_max_f32_e32 v150, v205, v207
	v_fma_f32 v208, s2, v170, v108
	v_fma_f32 v209, s3, v171, v109
	v_fma_f32 v210, s2, v172, v92
	v_fma_f32 v211, s3, v173, v93
	v_max3_f32 v148, v148, v149, v150
	v_max_f32_e32 v149, v208, v210
	v_max_f32_e32 v150, v209, v211
	v_fma_f32 v212, s2, v174, v110
	v_fma_f32 v213, s3, v175, v111
	v_fma_f32 v214, s2, v176, v94
	v_fma_f32 v215, s3, v177, v95
	v_max3_f32 v148, v148, v149, v150
	v_max_f32_e32 v149, v212, v214
	v_max_f32_e32 v150, v213, v215
	v_max3_f32 v237, v148, v149, v150
	v_mul_f32_e32 v236, s4, v0
	s_mov_b64 s[8:9], 0
